# v16 + residual GEMM: the workgroup touches each line of the residual tile once during the last K-loop iteration
# baseline (speedup 1.0000x reference)
; template <class Epi, class Sched, bool ALIGN_EPI = false, bool SP2 = false>
; __device__ __forceinline__ void gemm_phase(PG8_LAS unsigned char* lds, const Gemm g, const Sched& S, const Epi& E, const int tid) {
;     ...
;         for (int t = 0; t < nt; t += 2) {
;             const bool last = (t == nt - 2);
;             const char* a1 = cA + (size_t)(t + 1) * kstep;
;             const char* a2 = last ? nA : cA + (size_t)(t + 2) * kstep; const char* b2 = last ? nB : cB + (size_t)(t + 2) * kstep;
;             const char* a3 = a2 + kstep; const char* b3 = b2 + kstep;
;             if (last && has_next) S.a_ready(nxt);
;     DI void operator()(const pg8::f32x4 (&acc)[2][2][4][2], const pg8::Unit& u, int wr, int wc, int fr, int fq) const {
;     ...
; #pragma unroll
;                 for (int m = 0; m < 4; ++m) { const int row = row0 + ai * 128 + m * 16; xv[m] = *(const u32x4*)(X + (size_t)row * DM + col0 + bj * 128); st[m] = stat[row]; }
.LBB0_881:
	s_add_i32 s59, s34, 2
	s_add_u32 s60, s30, 0x80
	s_addc_u32 s35, s31, 0
	s_add_i32 s62, 0, 0x10000
	s_cmp_eq_u32 s52, s34
	s_cbranch_scc0 .Lres_touch_skip
	v_lshrrev_b32_e32 v218, 1, v152
	v_lshl_add_u32 v218, s55, 8, v218
	v_and_b32_e32 v206, 1, v152
	v_lshlrev_b32_e32 v206, 8, v206
	v_lshl_add_u32 v206, s56, 9, v206
	v_mov_b32_e32 v219, 0
	v_mov_b32_e32 v207, 0
	v_lshlrev_b64 v[218:219], 11, v[218:219]
	v_lshl_add_u64 v[218:219], v[218:219], 0, v[206:207]
	v_lshl_add_u64 v[218:219], s[24:25], 0, v[218:219]
	global_load_dword v209, v[218:219], off
	global_load_dword v209, v[218:219], off offset:128
